# adds: P3 peeled first K-iteration, dead v_mov_b64 removed from specialised silu path
# baseline (speedup 1.0000x reference)
; __device__ __forceinline__ float fsilu(float x) { return x * __builtin_amdgcn_rcpf(1.f + __expf(-x)); }
;     __device__ __forceinline__ void operator()(const f32x4 (&acc)[2][2][4][2], const pg8::Unit& u, int wr, int wc, int fr, int fq) const {
;     ...
;                 for (int m = 0; m < 4; ++m) { const int r = rowb + ai * 128 + m * 16; const float sc = rs[ai][m];
; #pragma unroll
;                     for (int bj = 0; bj < 2; ++bj) { u32x4 w;
; #pragma unroll
;                         for (int n = 0; n < 2; ++n) { f32x4 v = acc[ai][bj][m][n] * sc;
;                             if (cat == 0) v = v * QSCALE; else if (cat != 6) { v[0] = fsilu(v[0]); v[1] = fsilu(v[1]); v[2] = fsilu(v[2]); v[3] = fsilu(v[3]); }
;                             w[2 * n] = pk2(v[0], v[1]); w[2 * n + 1] = pk2(v[2], v[3]); }
;                         *(u32x4*)(base + (size_t)r * pitch + cb + bj * 128) = w; } }
.LBB0_233:
	s_and_b64 vcc, exec, s[42:43]
	s_cbranch_vccnz .Lbf16_q
	s_cmp_eq_u32 s47, 6
	s_cbranch_scc1 .Lbf16_plain
	s_cmp_lg_u32 s47, 6
	s_cselect_b64 s[6:7], -1, 0
	s_waitcnt lgkmcnt(0)
	v_pk_mul_f32 v[162:163], v[158:159], v[200:201] op_sel_hi:[1,0]
	v_cndmask_b32_e64 v158, 0, 1, s[6:7]
	v_pk_mul_f32 v[164:165], v[160:161], v[200:201] op_sel_hi:[1,0]
	v_cmp_ne_u32_e64 s[44:45], 1, v158
	s_movk_i32 s57, 0x4000
	v_mul_f32_e32 v158, 0xbfb8aa3b, v162
	v_mul_f32_e32 v159, 0xbfb8aa3b, v163
	v_mul_f32_e32 v160, 0xbfb8aa3b, v164
	v_mul_f32_e32 v161, 0xbfb8aa3b, v165
	v_exp_f32_e32 v158, v158
	v_exp_f32_e32 v159, v159
	v_exp_f32_e32 v160, v160
	v_exp_f32_e32 v161, v161
	v_add_f32_e32 v158, 1.0, v158
	v_add_f32_e32 v159, 1.0, v159
	v_add_f32_e32 v160, 1.0, v160
	v_add_f32_e32 v161, 1.0, v161
	v_rcp_f32_e32 v158, v158
	v_rcp_f32_e32 v160, v160
	v_rcp_f32_e32 v161, v161
	v_rcp_f32_e32 v159, v159
	v_pk_mul_f32 v[160:161], v[164:165], v[160:161]
	v_pk_mul_f32 v[158:159], v[162:163], v[158:159]
	v_mov_b32_e32 v166, v200
	v_mov_b32_e32 v167, v200
	v_mov_b32_e32 v162, v200
	v_mov_b32_e32 v163, v200
	v_pk_mul_f32 v[156:157], v[156:157], v[162:163]
	v_pk_mul_f32 v[154:155], v[154:155], v[166:167]
	v_mul_f32_e32 v162, 0xbfb8aa3b, v154
	v_mul_f32_e32 v163, 0xbfb8aa3b, v155
	v_mul_f32_e32 v164, 0xbfb8aa3b, v156
	v_mul_f32_e32 v165, 0xbfb8aa3b, v157
	v_exp_f32_e32 v162, v162
	v_exp_f32_e32 v163, v163
	v_exp_f32_e32 v164, v164
	v_exp_f32_e32 v165, v165
	v_add_f32_e32 v162, 1.0, v162
	v_add_f32_e32 v163, 1.0, v163
	v_add_f32_e32 v164, 1.0, v164
	v_add_f32_e32 v165, 1.0, v165
	v_rcp_f32_e32 v162, v162
	v_rcp_f32_e32 v164, v164
	v_rcp_f32_e32 v165, v165
	v_rcp_f32_e32 v163, v163
	v_pk_mul_f32 v[164:165], v[156:157], v[164:165]
	v_pk_mul_f32 v[162:163], v[154:155], v[162:163]
	s_add_u32 s6, s22, s60
	s_addc_u32 s7, s23, s61
	v_ashrrev_i32_e32 v203, 31, v202
	v_cvt_pk_bf16_f32 v154, v158, v159
	v_lshl_add_u64 v[158:159], v[202:203], 1, s[6:7]
	v_mad_i64_i32 v[156:157], s[6:7], s56, v192, 0
	v_cvt_pk_bf16_f32 v155, v160, v161
	v_lshl_add_u64 v[160:161], v[156:157], 1, v[158:159]
	v_cvt_pk_bf16_f32 v156, v162, v163
	v_cvt_pk_bf16_f32 v157, v164, v165
	global_store_dwordx4 v[160:161], v[154:157], off
	s_nop 1
	v_mov_b32_e32 v154, v200
	v_mov_b32_e32 v155, v200
	v_pk_mul_f32 v[156:157], v[152:153], v[154:155]
	v_pk_mul_f32 v[154:155], v[150:151], v[166:167]
	v_mul_f32_e32 v150, 0xbfb8aa3b, v154
	v_mul_f32_e32 v151, 0xbfb8aa3b, v155
	v_mul_f32_e32 v152, 0xbfb8aa3b, v156
	v_mul_f32_e32 v153, 0xbfb8aa3b, v157
	v_exp_f32_e32 v150, v150
	v_exp_f32_e32 v151, v151
	v_exp_f32_e32 v152, v152
	v_exp_f32_e32 v153, v153
	v_add_f32_e32 v150, 1.0, v150
	v_add_f32_e32 v151, 1.0, v151
	v_add_f32_e32 v152, 1.0, v152
	v_add_f32_e32 v153, 1.0, v153
	v_rcp_f32_e32 v150, v150
	v_rcp_f32_e32 v152, v152
	v_rcp_f32_e32 v153, v153
	v_rcp_f32_e32 v151, v151
	v_pk_mul_f32 v[152:153], v[156:157], v[152:153]
	v_pk_mul_f32 v[150:151], v[154:155], v[150:151]
	v_mov_b32_e32 v154, v200
	v_mov_b32_e32 v155, v200
	v_pk_mul_f32 v[148:149], v[148:149], v[154:155]
	v_pk_mul_f32 v[146:147], v[146:147], v[166:167]
	v_mul_f32_e32 v154, 0xbfb8aa3b, v146
	v_mul_f32_e32 v155, 0xbfb8aa3b, v147
	v_mul_f32_e32 v156, 0xbfb8aa3b, v148
	v_mul_f32_e32 v157, 0xbfb8aa3b, v149
	v_exp_f32_e32 v154, v154
	v_exp_f32_e32 v155, v155
	v_exp_f32_e32 v156, v156
	v_exp_f32_e32 v157, v157
	v_add_f32_e32 v154, 1.0, v154
	v_add_f32_e32 v155, 1.0, v155
	v_add_f32_e32 v156, 1.0, v156
	v_add_f32_e32 v157, 1.0, v157
	v_rcp_f32_e32 v154, v154
	v_rcp_f32_e32 v156, v156
	v_rcp_f32_e32 v157, v157
	v_rcp_f32_e32 v155, v155
	v_pk_mul_f32 v[156:157], v[148:149], v[156:157]
	v_pk_mul_f32 v[154:155], v[146:147], v[154:155]
	v_cvt_pk_bf16_f32 v146, v150, v151
	v_cvt_pk_bf16_f32 v147, v152, v153
	v_cvt_pk_bf16_f32 v148, v154, v155
	v_cvt_pk_bf16_f32 v149, v156, v157
	global_store_dwordx4 v[160:161], v[146:149], off offset:256
	s_nop 1
	v_pk_mul_f32 v[146:147], v[142:143], v[200:201] op_sel:[0,1]
	v_pk_mul_f32 v[148:149], v[144:145], v[200:201] op_sel:[0,1]
	v_mul_f32_e32 v142, 0xbfb8aa3b, v146
	v_mul_f32_e32 v143, 0xbfb8aa3b, v147
	v_mul_f32_e32 v144, 0xbfb8aa3b, v148
	v_mul_f32_e32 v145, 0xbfb8aa3b, v149
	v_exp_f32_e32 v142, v142
	v_exp_f32_e32 v143, v143
	v_exp_f32_e32 v144, v144
	v_exp_f32_e32 v145, v145
	v_add_f32_e32 v142, 1.0, v142
	v_add_f32_e32 v143, 1.0, v143
	v_add_f32_e32 v144, 1.0, v144
	v_add_f32_e32 v145, 1.0, v145
	v_rcp_f32_e32 v142, v142
	v_rcp_f32_e32 v144, v144
	v_rcp_f32_e32 v145, v145
	v_rcp_f32_e32 v143, v143
	v_pk_mul_f32 v[144:145], v[148:149], v[144:145]
	v_pk_mul_f32 v[142:143], v[146:147], v[142:143]
	v_mov_b32_e32 v200, v201
	v_mov_b32_e32 v146, v201
	v_mov_b32_e32 v147, v201
	v_pk_mul_f32 v[140:141], v[140:141], v[146:147]
	v_pk_mul_f32 v[138:139], v[138:139], v[200:201]
	v_mul_f32_e32 v146, 0xbfb8aa3b, v138
	v_mul_f32_e32 v147, 0xbfb8aa3b, v139
	v_mul_f32_e32 v148, 0xbfb8aa3b, v140
	v_mul_f32_e32 v149, 0xbfb8aa3b, v141
	v_exp_f32_e32 v146, v146
	v_exp_f32_e32 v147, v147
	v_exp_f32_e32 v148, v148
	v_exp_f32_e32 v149, v149
	v_add_f32_e32 v146, 1.0, v146
	v_add_f32_e32 v147, 1.0, v147
	v_add_f32_e32 v148, 1.0, v148
	v_add_f32_e32 v149, 1.0, v149
	v_rcp_f32_e32 v146, v146
	v_rcp_f32_e32 v148, v148
	v_rcp_f32_e32 v149, v149
	v_rcp_f32_e32 v147, v147
	v_pk_mul_f32 v[148:149], v[140:141], v[148:149]
	v_pk_mul_f32 v[146:147], v[138:139], v[146:147]
	v_add_u32_e32 v140, 16, v192
	v_mad_i64_i32 v[140:141], s[6:7], s56, v140, 0
	v_cvt_pk_bf16_f32 v138, v142, v143
	v_cvt_pk_bf16_f32 v139, v144, v145
	v_lshl_add_u64 v[142:143], v[140:141], 1, v[158:159]
	v_cvt_pk_bf16_f32 v140, v146, v147
	v_cvt_pk_bf16_f32 v141, v148, v149
; __device__ __forceinline__ float fsilu(float x) { return x * __builtin_amdgcn_rcpf(1.f + __expf(-x)); }
;     __device__ __forceinline__ void operator()(const f32x4 (&acc)[2][2][4][2], const pg8::Unit& u, int wr, int wc, int fr, int fq) const {
;     ...
;                 for (int m = 0; m < 4; ++m) { const int r = rowb + ai * 128 + m * 16; const float sc = rs[ai][m];
; #pragma unroll
;                     for (int bj = 0; bj < 2; ++bj) { u32x4 w;
; #pragma unroll
;                         for (int n = 0; n < 2; ++n) { f32x4 v = acc[ai][bj][m][n] * sc;
;                             if (cat == 0) v = v * QSCALE; else if (cat != 6) { v[0] = fsilu(v[0]); v[1] = fsilu(v[1]); v[2] = fsilu(v[2]); v[3] = fsilu(v[3]); }
;                             w[2 * n] = pk2(v[0], v[1]); w[2 * n + 1] = pk2(v[2], v[3]); }
;                         *(u32x4*)(base + (size_t)r * pitch + cb + bj * 128) = w; } }
	global_store_dwordx4 v[142:143], v[138:141], off
	s_nop 1
	v_mov_b32_e32 v138, v201
	v_mov_b32_e32 v139, v201
	v_pk_mul_f32 v[140:141], v[136:137], v[138:139]
	v_pk_mul_f32 v[138:139], v[134:135], v[200:201]
	v_mul_f32_e32 v134, 0xbfb8aa3b, v138
	v_mul_f32_e32 v135, 0xbfb8aa3b, v139
	v_mul_f32_e32 v136, 0xbfb8aa3b, v140
	v_mul_f32_e32 v137, 0xbfb8aa3b, v141
	v_exp_f32_e32 v134, v134
	v_exp_f32_e32 v135, v135
	v_exp_f32_e32 v136, v136
	v_exp_f32_e32 v137, v137
	v_add_f32_e32 v134, 1.0, v134
	v_add_f32_e32 v135, 1.0, v135
	v_add_f32_e32 v136, 1.0, v136
	v_add_f32_e32 v137, 1.0, v137
	v_rcp_f32_e32 v134, v134
	v_rcp_f32_e32 v136, v136
	v_rcp_f32_e32 v137, v137
	v_rcp_f32_e32 v135, v135
	v_pk_mul_f32 v[136:137], v[140:141], v[136:137]
	v_pk_mul_f32 v[134:135], v[138:139], v[134:135]
	v_mov_b32_e32 v138, v201
	v_mov_b32_e32 v139, v201
	v_pk_mul_f32 v[132:133], v[132:133], v[138:139]
	v_pk_mul_f32 v[130:131], v[130:131], v[200:201]
	v_mul_f32_e32 v138, 0xbfb8aa3b, v130
	v_mul_f32_e32 v139, 0xbfb8aa3b, v131
	v_mul_f32_e32 v140, 0xbfb8aa3b, v132
	v_mul_f32_e32 v141, 0xbfb8aa3b, v133
	v_exp_f32_e32 v138, v138
	v_exp_f32_e32 v139, v139
	v_exp_f32_e32 v140, v140
	v_exp_f32_e32 v141, v141
	v_add_f32_e32 v138, 1.0, v138
	v_add_f32_e32 v139, 1.0, v139
	v_add_f32_e32 v140, 1.0, v140
	v_add_f32_e32 v141, 1.0, v141
	v_rcp_f32_e32 v138, v138
	v_rcp_f32_e32 v140, v140
	v_rcp_f32_e32 v141, v141
	v_rcp_f32_e32 v139, v139
	v_pk_mul_f32 v[140:141], v[132:133], v[140:141]
	v_pk_mul_f32 v[138:139], v[130:131], v[138:139]
	v_cvt_pk_bf16_f32 v130, v134, v135
	v_cvt_pk_bf16_f32 v131, v136, v137
	v_cvt_pk_bf16_f32 v132, v138, v139
	v_cvt_pk_bf16_f32 v133, v140, v141
	global_store_dwordx4 v[142:143], v[130:133], off offset:256
	s_nop 1
	v_pk_mul_f32 v[130:131], v[126:127], v[198:199] op_sel_hi:[1,0]
	v_pk_mul_f32 v[132:133], v[128:129], v[198:199] op_sel_hi:[1,0]
	v_mul_f32_e32 v126, 0xbfb8aa3b, v130
	v_mul_f32_e32 v127, 0xbfb8aa3b, v131
	v_mul_f32_e32 v128, 0xbfb8aa3b, v132
	v_mul_f32_e32 v129, 0xbfb8aa3b, v133
	v_exp_f32_e32 v126, v126
	v_exp_f32_e32 v127, v127
	v_exp_f32_e32 v128, v128
	v_exp_f32_e32 v129, v129
	v_add_f32_e32 v126, 1.0, v126
	v_add_f32_e32 v127, 1.0, v127
	v_add_f32_e32 v128, 1.0, v128
	v_add_f32_e32 v129, 1.0, v129
	v_rcp_f32_e32 v126, v126
	v_rcp_f32_e32 v128, v128
	v_rcp_f32_e32 v129, v129
	v_rcp_f32_e32 v127, v127
	v_pk_mul_f32 v[128:129], v[132:133], v[128:129]
	v_pk_mul_f32 v[126:127], v[130:131], v[126:127]
	v_mov_b32_e32 v134, v198
	v_mov_b32_e32 v135, v198
	v_mov_b32_e32 v130, v198
	v_mov_b32_e32 v131, v198
	v_pk_mul_f32 v[124:125], v[124:125], v[130:131]
	v_pk_mul_f32 v[122:123], v[122:123], v[134:135]
	v_mul_f32_e32 v130, 0xbfb8aa3b, v122
	v_mul_f32_e32 v131, 0xbfb8aa3b, v123
	v_mul_f32_e32 v132, 0xbfb8aa3b, v124
	v_mul_f32_e32 v133, 0xbfb8aa3b, v125
	v_exp_f32_e32 v130, v130
	v_exp_f32_e32 v131, v131
	v_exp_f32_e32 v132, v132
	v_exp_f32_e32 v133, v133
	v_add_f32_e32 v130, 1.0, v130
	v_add_f32_e32 v131, 1.0, v131
	v_add_f32_e32 v132, 1.0, v132
	v_add_f32_e32 v133, 1.0, v133
	v_rcp_f32_e32 v130, v130
	v_rcp_f32_e32 v132, v132
	v_rcp_f32_e32 v133, v133
	v_rcp_f32_e32 v131, v131
	v_pk_mul_f32 v[132:133], v[124:125], v[132:133]
	v_pk_mul_f32 v[130:131], v[122:123], v[130:131]
	v_add_u32_e32 v124, 32, v192
	v_mad_i64_i32 v[124:125], s[6:7], s56, v124, 0
	v_cvt_pk_bf16_f32 v122, v126, v127
	v_cvt_pk_bf16_f32 v123, v128, v129
	v_lshl_add_u64 v[126:127], v[124:125], 1, v[158:159]
	v_cvt_pk_bf16_f32 v124, v130, v131
	v_cvt_pk_bf16_f32 v125, v132, v133
	global_store_dwordx4 v[126:127], v[122:125], off
	s_nop 1
	v_mov_b32_e32 v122, v198
	v_mov_b32_e32 v123, v198
	v_pk_mul_f32 v[124:125], v[120:121], v[122:123]
	v_pk_mul_f32 v[122:123], v[118:119], v[134:135]
	v_mul_f32_e32 v118, 0xbfb8aa3b, v122
	v_mul_f32_e32 v119, 0xbfb8aa3b, v123
	v_mul_f32_e32 v120, 0xbfb8aa3b, v124
	v_mul_f32_e32 v121, 0xbfb8aa3b, v125
	v_exp_f32_e32 v118, v118
	v_exp_f32_e32 v119, v119
	v_exp_f32_e32 v120, v120
	v_exp_f32_e32 v121, v121
	v_add_f32_e32 v118, 1.0, v118
	v_add_f32_e32 v119, 1.0, v119
	v_add_f32_e32 v120, 1.0, v120
	v_add_f32_e32 v121, 1.0, v121
	v_rcp_f32_e32 v118, v118
	v_rcp_f32_e32 v120, v120
	v_rcp_f32_e32 v121, v121
	v_rcp_f32_e32 v119, v119
	v_pk_mul_f32 v[120:121], v[124:125], v[120:121]
	v_pk_mul_f32 v[118:119], v[122:123], v[118:119]
	v_mov_b32_e32 v122, v198
	v_mov_b32_e32 v123, v198
	v_pk_mul_f32 v[116:117], v[116:117], v[122:123]
	v_pk_mul_f32 v[114:115], v[114:115], v[134:135]
	v_mul_f32_e32 v122, 0xbfb8aa3b, v114
	v_mul_f32_e32 v123, 0xbfb8aa3b, v115
	v_mul_f32_e32 v124, 0xbfb8aa3b, v116
	v_mul_f32_e32 v125, 0xbfb8aa3b, v117
	v_exp_f32_e32 v122, v122
	v_exp_f32_e32 v123, v123
	v_exp_f32_e32 v124, v124
	v_exp_f32_e32 v125, v125
	v_add_f32_e32 v122, 1.0, v122
	v_add_f32_e32 v123, 1.0, v123
	v_add_f32_e32 v124, 1.0, v124
	v_add_f32_e32 v125, 1.0, v125
	v_rcp_f32_e32 v122, v122
	v_rcp_f32_e32 v124, v124
	v_rcp_f32_e32 v125, v125
	v_rcp_f32_e32 v123, v123
	v_pk_mul_f32 v[124:125], v[116:117], v[124:125]
	v_pk_mul_f32 v[122:123], v[114:115], v[122:123]
	v_cvt_pk_bf16_f32 v114, v118, v119
	v_cvt_pk_bf16_f32 v115, v120, v121
	v_cvt_pk_bf16_f32 v116, v122, v123
	v_cvt_pk_bf16_f32 v117, v124, v125
	global_store_dwordx4 v[126:127], v[114:117], off offset:256
	s_nop 1
	v_pk_mul_f32 v[114:115], v[106:107], v[198:199] op_sel:[0,1]
	v_pk_mul_f32 v[116:117], v[108:109], v[198:199] op_sel:[0,1]
	v_mul_f32_e32 v106, 0xbfb8aa3b, v114
	v_mul_f32_e32 v107, 0xbfb8aa3b, v115
	v_mul_f32_e32 v108, 0xbfb8aa3b, v116
	v_mul_f32_e32 v109, 0xbfb8aa3b, v117
	v_exp_f32_e32 v106, v106
	v_exp_f32_e32 v107, v107
	v_exp_f32_e32 v108, v108
	v_exp_f32_e32 v109, v109
; __device__ __forceinline__ float fsilu(float x) { return x * __builtin_amdgcn_rcpf(1.f + __expf(-x)); }
;     __device__ __forceinline__ void operator()(const f32x4 (&acc)[2][2][4][2], const pg8::Unit& u, int wr, int wc, int fr, int fq) const {
;     ...
;                 for (int m = 0; m < 4; ++m) { const int r = rowb + ai * 128 + m * 16; const float sc = rs[ai][m];
; #pragma unroll
;                     for (int bj = 0; bj < 2; ++bj) { u32x4 w;
; #pragma unroll
;                         for (int n = 0; n < 2; ++n) { f32x4 v = acc[ai][bj][m][n] * sc;
;                             if (cat == 0) v = v * QSCALE; else if (cat != 6) { v[0] = fsilu(v[0]); v[1] = fsilu(v[1]); v[2] = fsilu(v[2]); v[3] = fsilu(v[3]); }
;                             w[2 * n] = pk2(v[0], v[1]); w[2 * n + 1] = pk2(v[2], v[3]); }
;                         *(u32x4*)(base + (size_t)r * pitch + cb + bj * 128) = w; } }
	v_add_f32_e32 v106, 1.0, v106
	v_add_f32_e32 v107, 1.0, v107
	v_add_f32_e32 v108, 1.0, v108
	v_add_f32_e32 v109, 1.0, v109
	v_rcp_f32_e32 v106, v106
	v_rcp_f32_e32 v108, v108
	v_rcp_f32_e32 v109, v109
	v_rcp_f32_e32 v107, v107
	v_pk_mul_f32 v[108:109], v[116:117], v[108:109]
	v_pk_mul_f32 v[106:107], v[114:115], v[106:107]
	v_mov_b32_e32 v198, v199
	v_mov_b32_e32 v114, v199
	v_mov_b32_e32 v115, v199
	v_pk_mul_f32 v[88:89], v[88:89], v[114:115]
	v_pk_mul_f32 v[86:87], v[86:87], v[198:199]
	v_mul_f32_e32 v114, 0xbfb8aa3b, v86
	v_mul_f32_e32 v115, 0xbfb8aa3b, v87
	v_mul_f32_e32 v116, 0xbfb8aa3b, v88
	v_mul_f32_e32 v117, 0xbfb8aa3b, v89
	v_exp_f32_e32 v114, v114
	v_exp_f32_e32 v115, v115
	v_exp_f32_e32 v116, v116
	v_exp_f32_e32 v117, v117
	v_add_f32_e32 v114, 1.0, v114
	v_add_f32_e32 v115, 1.0, v115
	v_add_f32_e32 v116, 1.0, v116
	v_add_f32_e32 v117, 1.0, v117
	v_rcp_f32_e32 v114, v114
	v_rcp_f32_e32 v116, v116
	v_rcp_f32_e32 v117, v117
	v_rcp_f32_e32 v115, v115
	v_pk_mul_f32 v[116:117], v[88:89], v[116:117]
	v_pk_mul_f32 v[114:115], v[86:87], v[114:115]
	v_add_u32_e32 v88, 48, v192
	v_mad_i64_i32 v[88:89], s[6:7], s56, v88, 0
	v_cvt_pk_bf16_f32 v86, v106, v107
	v_cvt_pk_bf16_f32 v87, v108, v109
	v_lshl_add_u64 v[106:107], v[88:89], 1, v[158:159]
	v_cvt_pk_bf16_f32 v88, v114, v115
	v_cvt_pk_bf16_f32 v89, v116, v117
	global_store_dwordx4 v[106:107], v[86:89], off
	s_nop 1
	v_mov_b32_e32 v86, v199
	v_mov_b32_e32 v87, v199
	v_pk_mul_f32 v[88:89], v[72:73], v[86:87]
	v_pk_mul_f32 v[86:87], v[70:71], v[198:199]
	v_mul_f32_e32 v70, 0xbfb8aa3b, v86
	v_mul_f32_e32 v71, 0xbfb8aa3b, v87
	v_mul_f32_e32 v72, 0xbfb8aa3b, v88
	v_mul_f32_e32 v73, 0xbfb8aa3b, v89
	v_exp_f32_e32 v70, v70
	v_exp_f32_e32 v71, v71
	v_exp_f32_e32 v72, v72
	v_exp_f32_e32 v73, v73
	v_add_f32_e32 v70, 1.0, v70
	v_add_f32_e32 v71, 1.0, v71
	v_add_f32_e32 v72, 1.0, v72
	v_add_f32_e32 v73, 1.0, v73
	v_rcp_f32_e32 v70, v70
	v_rcp_f32_e32 v72, v72
	v_rcp_f32_e32 v73, v73
	v_rcp_f32_e32 v71, v71
	v_pk_mul_f32 v[72:73], v[88:89], v[72:73]
	v_pk_mul_f32 v[70:71], v[86:87], v[70:71]
	v_mov_b32_e32 v86, v199
	v_mov_b32_e32 v87, v199
	v_pk_mul_f32 v[68:69], v[68:69], v[86:87]
	v_pk_mul_f32 v[66:67], v[66:67], v[198:199]
	v_mul_f32_e32 v86, 0xbfb8aa3b, v66
	v_mul_f32_e32 v87, 0xbfb8aa3b, v67
	v_mul_f32_e32 v88, 0xbfb8aa3b, v68
	v_mul_f32_e32 v89, 0xbfb8aa3b, v69
	v_exp_f32_e32 v86, v86
	v_exp_f32_e32 v87, v87
	v_exp_f32_e32 v88, v88
	v_exp_f32_e32 v89, v89
	v_add_f32_e32 v86, 1.0, v86
	v_add_f32_e32 v87, 1.0, v87
	v_add_f32_e32 v88, 1.0, v88
	v_add_f32_e32 v89, 1.0, v89
	v_rcp_f32_e32 v86, v86
	v_rcp_f32_e32 v88, v88
	v_rcp_f32_e32 v89, v89
	v_rcp_f32_e32 v87, v87
	v_pk_mul_f32 v[88:89], v[68:69], v[88:89]
	v_pk_mul_f32 v[86:87], v[66:67], v[86:87]
	v_cvt_pk_bf16_f32 v66, v70, v71
	v_cvt_pk_bf16_f32 v67, v72, v73
	v_cvt_pk_bf16_f32 v68, v86, v87
	v_cvt_pk_bf16_f32 v69, v88, v89
	global_store_dwordx4 v[106:107], v[66:69], off offset:256
	s_nop 1
	v_pk_mul_f32 v[66:67], v[62:63], v[196:197] op_sel_hi:[1,0]
	v_pk_mul_f32 v[68:69], v[64:65], v[196:197] op_sel_hi:[1,0]
	v_mul_f32_e32 v62, 0xbfb8aa3b, v66
	v_mul_f32_e32 v63, 0xbfb8aa3b, v67
	v_mul_f32_e32 v64, 0xbfb8aa3b, v68
	v_mul_f32_e32 v65, 0xbfb8aa3b, v69
	v_exp_f32_e32 v62, v62
	v_exp_f32_e32 v63, v63
	v_exp_f32_e32 v64, v64
	v_exp_f32_e32 v65, v65
	v_add_f32_e32 v62, 1.0, v62
	v_add_f32_e32 v63, 1.0, v63
	v_add_f32_e32 v64, 1.0, v64
	v_add_f32_e32 v65, 1.0, v65
	v_rcp_f32_e32 v62, v62
	v_rcp_f32_e32 v64, v64
	v_rcp_f32_e32 v65, v65
	v_rcp_f32_e32 v63, v63
	v_pk_mul_f32 v[64:65], v[68:69], v[64:65]
	v_pk_mul_f32 v[62:63], v[66:67], v[62:63]
	v_mov_b32_e32 v70, v196
	v_mov_b32_e32 v71, v196
	v_mov_b32_e32 v66, v196
	v_mov_b32_e32 v67, v196
	v_pk_mul_f32 v[60:61], v[60:61], v[66:67]
	v_pk_mul_f32 v[58:59], v[58:59], v[70:71]
	v_mul_f32_e32 v66, 0xbfb8aa3b, v58
	v_mul_f32_e32 v67, 0xbfb8aa3b, v59
	v_mul_f32_e32 v68, 0xbfb8aa3b, v60
	v_mul_f32_e32 v69, 0xbfb8aa3b, v61
	v_exp_f32_e32 v66, v66
	v_exp_f32_e32 v67, v67
	v_exp_f32_e32 v68, v68
	v_exp_f32_e32 v69, v69
	v_add_f32_e32 v66, 1.0, v66
	v_add_f32_e32 v67, 1.0, v67
	v_add_f32_e32 v68, 1.0, v68
	v_add_f32_e32 v69, 1.0, v69
	v_rcp_f32_e32 v66, v66
	v_rcp_f32_e32 v68, v68
	v_rcp_f32_e32 v69, v69
	v_rcp_f32_e32 v67, v67
	v_pk_mul_f32 v[68:69], v[60:61], v[68:69]
	v_pk_mul_f32 v[66:67], v[58:59], v[66:67]
	v_add_u32_e32 v60, 0x80, v192
	v_mad_i64_i32 v[60:61], s[6:7], s56, v60, 0
	v_cvt_pk_bf16_f32 v58, v62, v63
	v_cvt_pk_bf16_f32 v59, v64, v65
	v_lshl_add_u64 v[62:63], v[60:61], 1, v[158:159]
	v_cvt_pk_bf16_f32 v60, v66, v67
	v_cvt_pk_bf16_f32 v61, v68, v69
	global_store_dwordx4 v[62:63], v[58:61], off
	s_nop 1
	v_mov_b32_e32 v58, v196
	v_mov_b32_e32 v59, v196
	v_pk_mul_f32 v[60:61], v[56:57], v[58:59]
	v_pk_mul_f32 v[58:59], v[54:55], v[70:71]
	v_mul_f32_e32 v54, 0xbfb8aa3b, v58
	v_mul_f32_e32 v55, 0xbfb8aa3b, v59
	v_mul_f32_e32 v56, 0xbfb8aa3b, v60
	v_mul_f32_e32 v57, 0xbfb8aa3b, v61
	v_exp_f32_e32 v54, v54
	v_exp_f32_e32 v55, v55
	v_exp_f32_e32 v56, v56
	v_exp_f32_e32 v57, v57
	v_add_f32_e32 v54, 1.0, v54
	v_add_f32_e32 v55, 1.0, v55
	v_add_f32_e32 v56, 1.0, v56
	v_add_f32_e32 v57, 1.0, v57
	v_rcp_f32_e32 v54, v54
	v_rcp_f32_e32 v56, v56
	v_rcp_f32_e32 v57, v57
	v_rcp_f32_e32 v55, v55
	v_pk_mul_f32 v[56:57], v[60:61], v[56:57]
	v_pk_mul_f32 v[54:55], v[58:59], v[54:55]
	v_mov_b32_e32 v58, v196
	v_mov_b32_e32 v59, v196
	v_pk_mul_f32 v[52:53], v[52:53], v[58:59]
	v_pk_mul_f32 v[50:51], v[50:51], v[70:71]
	v_mul_f32_e32 v58, 0xbfb8aa3b, v50
	v_mul_f32_e32 v59, 0xbfb8aa3b, v51
	v_mul_f32_e32 v60, 0xbfb8aa3b, v52
	v_mul_f32_e32 v61, 0xbfb8aa3b, v53
	v_exp_f32_e32 v58, v58
	v_exp_f32_e32 v59, v59
; __device__ __forceinline__ float fsilu(float x) { return x * __builtin_amdgcn_rcpf(1.f + __expf(-x)); }
;     __device__ __forceinline__ void operator()(const f32x4 (&acc)[2][2][4][2], const pg8::Unit& u, int wr, int wc, int fr, int fq) const {
;     ...
;                 for (int m = 0; m < 4; ++m) { const int r = rowb + ai * 128 + m * 16; const float sc = rs[ai][m];
; #pragma unroll
;                     for (int bj = 0; bj < 2; ++bj) { u32x4 w;
; #pragma unroll
;                         for (int n = 0; n < 2; ++n) { f32x4 v = acc[ai][bj][m][n] * sc;
;                             if (cat == 0) v = v * QSCALE; else if (cat != 6) { v[0] = fsilu(v[0]); v[1] = fsilu(v[1]); v[2] = fsilu(v[2]); v[3] = fsilu(v[3]); }
;                             w[2 * n] = pk2(v[0], v[1]); w[2 * n + 1] = pk2(v[2], v[3]); }
;                         *(u32x4*)(base + (size_t)r * pitch + cb + bj * 128) = w; } }
	v_exp_f32_e32 v60, v60
	v_exp_f32_e32 v61, v61
	v_add_f32_e32 v58, 1.0, v58
	v_add_f32_e32 v59, 1.0, v59
	v_add_f32_e32 v60, 1.0, v60
	v_add_f32_e32 v61, 1.0, v61
	v_rcp_f32_e32 v58, v58
	v_rcp_f32_e32 v60, v60
	v_rcp_f32_e32 v61, v61
	v_rcp_f32_e32 v59, v59
	v_pk_mul_f32 v[60:61], v[52:53], v[60:61]
	v_pk_mul_f32 v[58:59], v[50:51], v[58:59]
	v_cvt_pk_bf16_f32 v50, v54, v55
	v_cvt_pk_bf16_f32 v51, v56, v57
	v_cvt_pk_bf16_f32 v52, v58, v59
	v_cvt_pk_bf16_f32 v53, v60, v61
	global_store_dwordx4 v[62:63], v[50:53], off offset:256
	s_nop 1
	v_pk_mul_f32 v[50:51], v[46:47], v[196:197] op_sel:[0,1]
	v_pk_mul_f32 v[52:53], v[48:49], v[196:197] op_sel:[0,1]
	v_mul_f32_e32 v46, 0xbfb8aa3b, v50
	v_mul_f32_e32 v47, 0xbfb8aa3b, v51
	v_mul_f32_e32 v48, 0xbfb8aa3b, v52
	v_mul_f32_e32 v49, 0xbfb8aa3b, v53
	v_exp_f32_e32 v46, v46
	v_exp_f32_e32 v47, v47
	v_exp_f32_e32 v48, v48
	v_exp_f32_e32 v49, v49
	v_add_f32_e32 v46, 1.0, v46
	v_add_f32_e32 v47, 1.0, v47
	v_add_f32_e32 v48, 1.0, v48
	v_add_f32_e32 v49, 1.0, v49
	v_rcp_f32_e32 v46, v46
	v_rcp_f32_e32 v48, v48
	v_rcp_f32_e32 v49, v49
	v_rcp_f32_e32 v47, v47
	v_pk_mul_f32 v[48:49], v[52:53], v[48:49]
	v_pk_mul_f32 v[46:47], v[50:51], v[46:47]
	v_mov_b32_e32 v196, v197
	v_mov_b32_e32 v50, v197
	v_mov_b32_e32 v51, v197
	v_pk_mul_f32 v[44:45], v[44:45], v[50:51]
	v_pk_mul_f32 v[42:43], v[42:43], v[196:197]
	v_mul_f32_e32 v50, 0xbfb8aa3b, v42
	v_mul_f32_e32 v51, 0xbfb8aa3b, v43
	v_mul_f32_e32 v52, 0xbfb8aa3b, v44
	v_mul_f32_e32 v53, 0xbfb8aa3b, v45
	v_exp_f32_e32 v50, v50
	v_exp_f32_e32 v51, v51
	v_exp_f32_e32 v52, v52
	v_exp_f32_e32 v53, v53
	v_add_f32_e32 v50, 1.0, v50
	v_add_f32_e32 v51, 1.0, v51
	v_add_f32_e32 v52, 1.0, v52
	v_add_f32_e32 v53, 1.0, v53
	v_rcp_f32_e32 v50, v50
	v_rcp_f32_e32 v52, v52
	v_rcp_f32_e32 v53, v53
	v_rcp_f32_e32 v51, v51
	v_pk_mul_f32 v[52:53], v[44:45], v[52:53]
	v_pk_mul_f32 v[50:51], v[42:43], v[50:51]
	v_add_u32_e32 v44, 0x90, v192
	v_mad_i64_i32 v[44:45], s[6:7], s56, v44, 0
	v_cvt_pk_bf16_f32 v42, v46, v47
	v_cvt_pk_bf16_f32 v43, v48, v49
	v_lshl_add_u64 v[46:47], v[44:45], 1, v[158:159]
	v_cvt_pk_bf16_f32 v44, v50, v51
	v_cvt_pk_bf16_f32 v45, v52, v53
	global_store_dwordx4 v[46:47], v[42:45], off
	s_nop 1
	v_mov_b32_e32 v42, v197
	v_mov_b32_e32 v43, v197
	v_pk_mul_f32 v[44:45], v[40:41], v[42:43]
	v_pk_mul_f32 v[42:43], v[38:39], v[196:197]
	v_mul_f32_e32 v38, 0xbfb8aa3b, v42
	v_mul_f32_e32 v39, 0xbfb8aa3b, v43
	v_mul_f32_e32 v40, 0xbfb8aa3b, v44
	v_mul_f32_e32 v41, 0xbfb8aa3b, v45
	v_exp_f32_e32 v38, v38
	v_exp_f32_e32 v39, v39
	v_exp_f32_e32 v40, v40
	v_exp_f32_e32 v41, v41
	v_add_f32_e32 v38, 1.0, v38
	v_add_f32_e32 v39, 1.0, v39
	v_add_f32_e32 v40, 1.0, v40
	v_add_f32_e32 v41, 1.0, v41
	v_rcp_f32_e32 v38, v38
	v_rcp_f32_e32 v40, v40
	v_rcp_f32_e32 v41, v41
	v_rcp_f32_e32 v39, v39
	v_pk_mul_f32 v[40:41], v[44:45], v[40:41]
	v_pk_mul_f32 v[38:39], v[42:43], v[38:39]
	v_mov_b32_e32 v42, v197
	v_mov_b32_e32 v43, v197
	v_pk_mul_f32 v[36:37], v[36:37], v[42:43]
	v_pk_mul_f32 v[34:35], v[34:35], v[196:197]
	v_mul_f32_e32 v42, 0xbfb8aa3b, v34
	v_mul_f32_e32 v43, 0xbfb8aa3b, v35
	v_mul_f32_e32 v44, 0xbfb8aa3b, v36
	v_mul_f32_e32 v45, 0xbfb8aa3b, v37
	v_exp_f32_e32 v42, v42
	v_exp_f32_e32 v43, v43
	v_exp_f32_e32 v44, v44
	v_exp_f32_e32 v45, v45
	v_add_f32_e32 v42, 1.0, v42
	v_add_f32_e32 v43, 1.0, v43
	v_add_f32_e32 v44, 1.0, v44
	v_add_f32_e32 v45, 1.0, v45
	v_rcp_f32_e32 v42, v42
	v_rcp_f32_e32 v44, v44
	v_rcp_f32_e32 v45, v45
	v_rcp_f32_e32 v43, v43
	v_pk_mul_f32 v[44:45], v[36:37], v[44:45]
	v_pk_mul_f32 v[42:43], v[34:35], v[42:43]
	v_cvt_pk_bf16_f32 v34, v38, v39
	v_cvt_pk_bf16_f32 v35, v40, v41
	v_cvt_pk_bf16_f32 v36, v42, v43
	v_cvt_pk_bf16_f32 v37, v44, v45
	global_store_dwordx4 v[46:47], v[34:37], off offset:256
	s_nop 1
	v_pk_mul_f32 v[34:35], v[30:31], v[194:195] op_sel_hi:[1,0]
	v_pk_mul_f32 v[36:37], v[32:33], v[194:195] op_sel_hi:[1,0]
	v_mul_f32_e32 v30, 0xbfb8aa3b, v34
	v_mul_f32_e32 v31, 0xbfb8aa3b, v35
	v_mul_f32_e32 v32, 0xbfb8aa3b, v36
	v_mul_f32_e32 v33, 0xbfb8aa3b, v37
	v_exp_f32_e32 v30, v30
	v_exp_f32_e32 v31, v31
	v_exp_f32_e32 v32, v32
	v_exp_f32_e32 v33, v33
	v_add_f32_e32 v30, 1.0, v30
	v_add_f32_e32 v31, 1.0, v31
	v_add_f32_e32 v32, 1.0, v32
	v_add_f32_e32 v33, 1.0, v33
	v_rcp_f32_e32 v30, v30
	v_rcp_f32_e32 v32, v32
	v_rcp_f32_e32 v33, v33
	v_rcp_f32_e32 v31, v31
	v_pk_mul_f32 v[32:33], v[36:37], v[32:33]
	v_pk_mul_f32 v[30:31], v[34:35], v[30:31]
	v_mov_b32_e32 v38, v194
	v_mov_b32_e32 v39, v194
	v_mov_b32_e32 v34, v194
	v_mov_b32_e32 v35, v194
	v_pk_mul_f32 v[28:29], v[28:29], v[34:35]
	v_pk_mul_f32 v[26:27], v[26:27], v[38:39]
	v_mul_f32_e32 v34, 0xbfb8aa3b, v26
	v_mul_f32_e32 v35, 0xbfb8aa3b, v27
	v_mul_f32_e32 v36, 0xbfb8aa3b, v28
	v_mul_f32_e32 v37, 0xbfb8aa3b, v29
	v_exp_f32_e32 v34, v34
	v_exp_f32_e32 v35, v35
	v_exp_f32_e32 v36, v36
	v_exp_f32_e32 v37, v37
	v_add_f32_e32 v34, 1.0, v34
	v_add_f32_e32 v35, 1.0, v35
	v_add_f32_e32 v36, 1.0, v36
	v_add_f32_e32 v37, 1.0, v37
	v_rcp_f32_e32 v34, v34
	v_rcp_f32_e32 v36, v36
	v_rcp_f32_e32 v37, v37
	v_rcp_f32_e32 v35, v35
	v_pk_mul_f32 v[36:37], v[28:29], v[36:37]
; __device__ __forceinline__ float fsilu(float x) { return x * __builtin_amdgcn_rcpf(1.f + __expf(-x)); }
;     __device__ __forceinline__ void operator()(const f32x4 (&acc)[2][2][4][2], const pg8::Unit& u, int wr, int wc, int fr, int fq) const {
;     ...
;                 for (int m = 0; m < 4; ++m) { const int r = rowb + ai * 128 + m * 16; const float sc = rs[ai][m];
; #pragma unroll
;                     for (int bj = 0; bj < 2; ++bj) { u32x4 w;
; #pragma unroll
;                         for (int n = 0; n < 2; ++n) { f32x4 v = acc[ai][bj][m][n] * sc;
;                             if (cat == 0) v = v * QSCALE; else if (cat != 6) { v[0] = fsilu(v[0]); v[1] = fsilu(v[1]); v[2] = fsilu(v[2]); v[3] = fsilu(v[3]); }
;                             w[2 * n] = pk2(v[0], v[1]); w[2 * n + 1] = pk2(v[2], v[3]); }
;                         *(u32x4*)(base + (size_t)r * pitch + cb + bj * 128) = w; } }
	v_pk_mul_f32 v[34:35], v[26:27], v[34:35]
	v_add_u32_e32 v28, 0xa0, v192
	v_mad_i64_i32 v[28:29], s[6:7], s56, v28, 0
	v_cvt_pk_bf16_f32 v26, v30, v31
	v_cvt_pk_bf16_f32 v27, v32, v33
	v_lshl_add_u64 v[30:31], v[28:29], 1, v[158:159]
	v_cvt_pk_bf16_f32 v28, v34, v35
	v_cvt_pk_bf16_f32 v29, v36, v37
	global_store_dwordx4 v[30:31], v[26:29], off
	s_nop 1
	v_mov_b32_e32 v26, v194
	v_mov_b32_e32 v27, v194
	v_pk_mul_f32 v[28:29], v[24:25], v[26:27]
	v_pk_mul_f32 v[26:27], v[22:23], v[38:39]
	v_mul_f32_e32 v22, 0xbfb8aa3b, v26
	v_mul_f32_e32 v23, 0xbfb8aa3b, v27
	v_mul_f32_e32 v24, 0xbfb8aa3b, v28
	v_mul_f32_e32 v25, 0xbfb8aa3b, v29
	v_exp_f32_e32 v22, v22
	v_exp_f32_e32 v23, v23
	v_exp_f32_e32 v24, v24
	v_exp_f32_e32 v25, v25
	v_add_f32_e32 v22, 1.0, v22
	v_add_f32_e32 v23, 1.0, v23
	v_add_f32_e32 v24, 1.0, v24
	v_add_f32_e32 v25, 1.0, v25
	v_rcp_f32_e32 v22, v22
	v_rcp_f32_e32 v24, v24
	v_rcp_f32_e32 v25, v25
	v_rcp_f32_e32 v23, v23
	v_pk_mul_f32 v[24:25], v[28:29], v[24:25]
	v_pk_mul_f32 v[22:23], v[26:27], v[22:23]
	v_mov_b32_e32 v26, v194
	v_mov_b32_e32 v27, v194
	v_pk_mul_f32 v[20:21], v[20:21], v[26:27]
	v_pk_mul_f32 v[18:19], v[18:19], v[38:39]
	v_mul_f32_e32 v26, 0xbfb8aa3b, v18
	v_mul_f32_e32 v27, 0xbfb8aa3b, v19
	v_mul_f32_e32 v28, 0xbfb8aa3b, v20
	v_mul_f32_e32 v29, 0xbfb8aa3b, v21
	v_exp_f32_e32 v26, v26
	v_exp_f32_e32 v27, v27
	v_exp_f32_e32 v28, v28
	v_exp_f32_e32 v29, v29
	v_add_f32_e32 v26, 1.0, v26
	v_add_f32_e32 v27, 1.0, v27
	v_add_f32_e32 v28, 1.0, v28
	v_add_f32_e32 v29, 1.0, v29
	v_rcp_f32_e32 v26, v26
	v_rcp_f32_e32 v28, v28
	v_rcp_f32_e32 v29, v29
	v_rcp_f32_e32 v27, v27
	v_pk_mul_f32 v[28:29], v[20:21], v[28:29]
	v_pk_mul_f32 v[26:27], v[18:19], v[26:27]
	v_cvt_pk_bf16_f32 v18, v22, v23
	v_cvt_pk_bf16_f32 v19, v24, v25
	v_cvt_pk_bf16_f32 v20, v26, v27
	v_cvt_pk_bf16_f32 v21, v28, v29
	global_store_dwordx4 v[30:31], v[18:21], off offset:256
	s_nop 1
	v_pk_mul_f32 v[18:19], v[14:15], v[194:195] op_sel:[0,1]
	v_pk_mul_f32 v[20:21], v[16:17], v[194:195] op_sel:[0,1]
	v_mul_f32_e32 v14, 0xbfb8aa3b, v18
	v_mul_f32_e32 v15, 0xbfb8aa3b, v19
	v_mul_f32_e32 v16, 0xbfb8aa3b, v20
	v_mul_f32_e32 v17, 0xbfb8aa3b, v21
	v_exp_f32_e32 v14, v14
	v_exp_f32_e32 v15, v15
	v_exp_f32_e32 v16, v16
	v_exp_f32_e32 v17, v17
	v_add_f32_e32 v14, 1.0, v14
	v_add_f32_e32 v15, 1.0, v15
	v_add_f32_e32 v16, 1.0, v16
	v_add_f32_e32 v17, 1.0, v17
	v_rcp_f32_e32 v14, v14
	v_rcp_f32_e32 v16, v16
	v_rcp_f32_e32 v17, v17
	v_rcp_f32_e32 v15, v15
	v_pk_mul_f32 v[16:17], v[20:21], v[16:17]
	v_pk_mul_f32 v[14:15], v[18:19], v[14:15]
	v_mov_b32_e32 v194, v195
	v_mov_b32_e32 v18, v195
	v_mov_b32_e32 v19, v195
	v_pk_mul_f32 v[12:13], v[12:13], v[18:19]
	v_pk_mul_f32 v[10:11], v[10:11], v[194:195]
	v_mul_f32_e32 v18, 0xbfb8aa3b, v10
	v_mul_f32_e32 v19, 0xbfb8aa3b, v11
	v_mul_f32_e32 v20, 0xbfb8aa3b, v12
	v_mul_f32_e32 v21, 0xbfb8aa3b, v13
	v_exp_f32_e32 v18, v18
	v_exp_f32_e32 v19, v19
	v_exp_f32_e32 v20, v20
	v_exp_f32_e32 v21, v21
	v_add_f32_e32 v18, 1.0, v18
	v_add_f32_e32 v19, 1.0, v19
	v_add_f32_e32 v20, 1.0, v20
	v_add_f32_e32 v21, 1.0, v21
	v_rcp_f32_e32 v18, v18
	v_rcp_f32_e32 v20, v20
	v_rcp_f32_e32 v21, v21
	v_rcp_f32_e32 v19, v19
	v_pk_mul_f32 v[20:21], v[12:13], v[20:21]
	v_pk_mul_f32 v[18:19], v[10:11], v[18:19]
	v_add_u32_e32 v12, 0xb0, v192
	v_mad_i64_i32 v[12:13], s[6:7], s56, v12, 0
	v_cvt_pk_bf16_f32 v10, v14, v15
	v_cvt_pk_bf16_f32 v11, v16, v17
	v_lshl_add_u64 v[14:15], v[12:13], 1, v[158:159]
	v_cvt_pk_bf16_f32 v12, v18, v19
	v_cvt_pk_bf16_f32 v13, v20, v21
	global_store_dwordx4 v[14:15], v[10:13], off
	s_nop 1
	v_mov_b32_e32 v10, v195
	v_mov_b32_e32 v11, v195
	v_pk_mul_f32 v[12:13], v[8:9], v[10:11]
	v_pk_mul_f32 v[10:11], v[6:7], v[194:195]
	v_mul_f32_e32 v6, 0xbfb8aa3b, v10
	v_mul_f32_e32 v7, 0xbfb8aa3b, v11
	v_mul_f32_e32 v8, 0xbfb8aa3b, v12
	v_mul_f32_e32 v9, 0xbfb8aa3b, v13
	v_exp_f32_e32 v6, v6
	v_exp_f32_e32 v7, v7
	v_exp_f32_e32 v8, v8
	v_exp_f32_e32 v9, v9
	v_add_f32_e32 v6, 1.0, v6
	v_add_f32_e32 v7, 1.0, v7
	v_add_f32_e32 v8, 1.0, v8
	v_add_f32_e32 v9, 1.0, v9
	v_rcp_f32_e32 v6, v6
	v_rcp_f32_e32 v8, v8
	v_rcp_f32_e32 v9, v9
	v_rcp_f32_e32 v7, v7
	v_pk_mul_f32 v[8:9], v[12:13], v[8:9]
	v_pk_mul_f32 v[6:7], v[10:11], v[6:7]
	v_mov_b32_e32 v10, v195
	v_mov_b32_e32 v11, v195
	v_pk_mul_f32 v[4:5], v[4:5], v[10:11]
	v_pk_mul_f32 v[2:3], v[2:3], v[194:195]
	v_mul_f32_e32 v10, 0xbfb8aa3b, v2
	v_mul_f32_e32 v11, 0xbfb8aa3b, v3
	v_mul_f32_e32 v12, 0xbfb8aa3b, v4
	v_mul_f32_e32 v13, 0xbfb8aa3b, v5
	v_exp_f32_e32 v10, v10
	v_exp_f32_e32 v11, v11
	v_exp_f32_e32 v12, v12
	v_exp_f32_e32 v13, v13
	v_add_f32_e32 v10, 1.0, v10
	v_add_f32_e32 v11, 1.0, v11
	v_add_f32_e32 v12, 1.0, v12
	v_add_f32_e32 v13, 1.0, v13
	v_rcp_f32_e32 v10, v10
	v_rcp_f32_e32 v12, v12
	v_rcp_f32_e32 v13, v13
	v_rcp_f32_e32 v11, v11
	v_pk_mul_f32 v[12:13], v[4:5], v[12:13]
	v_pk_mul_f32 v[10:11], v[2:3], v[10:11]
	v_cvt_pk_bf16_f32 v2, v6, v7
	v_cvt_pk_bf16_f32 v3, v8, v9
	v_cvt_pk_bf16_f32 v4, v10, v11
	v_cvt_pk_bf16_f32 v5, v12, v13
	global_store_dwordx4 v[14:15], v[2:5], off offset:256
	s_nop 1
	s_branch .Lbf16_join

; #define PG8_STAGE(bufoff, gbase, voff) do { _Pragma("unroll") for (int _i = 0; _i < 2; ++_i) \
;         __builtin_amdgcn_global_load_lds((const unsigned*)((const char*)(gbase) + (voff)[_i]), (PG8_LAS unsigned*)(lds + (bufoff) + ldsw + _i * 8192), 16, 0, 0); } while (0)
; #define PG8_LDA(dst, b, h) do { _Pragma("unroll") for (int m = 0; m < 4; ++m) _Pragma("unroll") for (int k = 0; k < 2; ++k) dst[m][k] = *(const PG8_LAS bf16x8*)(lds + PG8_SA(b, h) + aoff + m * 2048 + k * 1024); } while (0)
; #define PG8_LDB(dst, b, h) do { _Pragma("unroll") for (int n = 0; n < 2; ++n) _Pragma("unroll") for (int k = 0; k < 2; ++k) dst[n][k] = *(const PG8_LAS bf16x8*)(lds + PG8_SB(b, h) + boff + n * 2048 + k * 1024); } while (0)
; #define PG8_SCHED __builtin_amdgcn_sched_barrier(0)
;     __device__ __forceinline__ bool next(int i, pg8::Unit& u) const { if (i != 0) return false; u.pm = pm; u.pn = pn; return true; }
; template <class Epi, class Sched, bool ALIGN_EPI = false, bool SP2 = false>
; __device__ __forceinline__ void gemm_phase(PG8_LAS unsigned char* lds, const Gemm g, const Sched& S, const Epi& E) {
;     ...
;         const bool has_next = S.next(ui + 1, nxt);
;         const char* nA = has_next ? (const char*)g.A + (size_t)nxt.pm * tstep : cA; const char* nB = has_next ? (const char*)g.Bt + (size_t)nxt.pn * tstep : cB;
;         for (int t = 0; t < nt; t += 2) {
;             const bool last = (t == nt - 2);
;             const char* a1 = cA + (size_t)(t + 1) * kstep;
;             const char* a2 = last ? nA : cA + (size_t)(t + 2) * kstep; const char* b2 = last ? nB : cB + (size_t)(t + 2) * kstep;
;             const char* a3 = a2 + kstep; const char* b3 = b2 + kstep;
;             if (last && has_next) S.a_ready(nxt);
;             if constexpr (SP2) {
;             PG8_LDB(B0, 0, 0); PG8_LDB(B1, 0, 1); PG8_SCHED; PG8_LDA(At, 0, 0); PG8_STAGE(PG8_SA(1, 1), a1 + hstep, voffA);
;     ...
;         for (int a = 0; a < 2; ++a)
; #pragma unroll
;             for (int b = 0; b < 2; ++b)
; #pragma unroll
;                 for (int m = 0; m < 4; ++m)
; #pragma unroll
;                     for (int n = 0; n < 2; ++n) acc[a][b][m][n] = (f32x4){0.f, 0.f, 0.f, 0.f};
.LBB0_984:
	s_ashr_i32 s15, s14, 31
	s_lshl_b64 s[22:23], s[14:15], 19
	v_readlane_b32 s0, v243, 27
	s_add_u32 s22, s0, s22
	v_readlane_b32 s0, v243, 28
	s_addc_u32 s23, s0, s23
	s_and_b64 s[40:41], s[38:39], exec
	s_cselect_b32 s15, s23, s43
	s_cselect_b32 s35, s22, s42
	s_ashr_i32 s13, s12, 31
	s_lshl_b64 s[40:41], s[12:13], 19
	s_add_u32 s40, s20, s40
	s_addc_u32 s41, s21, s41
	s_and_b64 s[46:47], s[38:39], exec
	s_cselect_b32 s13, s41, s45
	s_cselect_b32 s58, s40, s44
	s_add_u32 s42, s42, 0x40080
	s_addc_u32 s43, s43, 0
	s_add_u32 s59, s44, 0x100
	v_mov_b32_e32 v2, 0
	s_addc_u32 s60, s45, 0
	s_mov_b32 s61, -2
	s_waitcnt lgkmcnt(0)
	v_mov_b32_e32 v3, v2
	v_mov_b32_e32 v4, v2
	v_mov_b32_e32 v5, v2
	v_mov_b32_e32 v6, v2
	v_mov_b32_e32 v7, v2
	v_mov_b32_e32 v8, v2
	v_mov_b32_e32 v9, v2
	v_mov_b32_e32 v18, v2
	v_mov_b32_e32 v19, v2
	v_mov_b32_e32 v20, v2
	v_mov_b32_e32 v21, v2
	v_mov_b32_e32 v22, v2
	v_mov_b32_e32 v23, v2
	v_mov_b32_e32 v24, v2
	v_mov_b32_e32 v25, v2
	v_mov_b32_e32 v34, v2
	v_mov_b32_e32 v35, v2
	v_mov_b32_e32 v36, v2
	v_mov_b32_e32 v37, v2
	v_mov_b32_e32 v38, v2
	v_mov_b32_e32 v39, v2
	v_mov_b32_e32 v40, v2
	v_mov_b32_e32 v41, v2
	v_mov_b32_e32 v50, v2
	v_mov_b32_e32 v51, v2
	v_mov_b32_e32 v52, v2
	v_mov_b32_e32 v53, v2
	v_mov_b32_e32 v54, v2
	v_mov_b32_e32 v55, v2
	v_mov_b32_e32 v56, v2
	v_mov_b32_e32 v57, v2
	v_mov_b32_e32 v10, v2
	v_mov_b32_e32 v11, v2
	v_mov_b32_e32 v12, v2
	v_mov_b32_e32 v13, v2
	v_mov_b32_e32 v14, v2
	v_mov_b32_e32 v15, v2
	v_mov_b32_e32 v16, v2
	v_mov_b32_e32 v17, v2
	v_mov_b32_e32 v26, v2
	v_mov_b32_e32 v27, v2
	v_mov_b32_e32 v28, v2
	v_mov_b32_e32 v29, v2
	v_mov_b32_e32 v30, v2
	v_mov_b32_e32 v31, v2
	v_mov_b32_e32 v32, v2
	v_mov_b32_e32 v33, v2
	v_mov_b32_e32 v42, v2
	v_mov_b32_e32 v43, v2
	v_mov_b32_e32 v44, v2
	v_mov_b32_e32 v45, v2
	v_mov_b32_e32 v46, v2
	v_mov_b32_e32 v47, v2
	v_mov_b32_e32 v48, v2
	v_mov_b32_e32 v49, v2
	v_mov_b32_e32 v58, v2
	v_mov_b32_e32 v59, v2
	v_mov_b32_e32 v60, v2
	v_mov_b32_e32 v61, v2
	v_mov_b32_e32 v62, v2
	v_mov_b32_e32 v63, v2
	v_mov_b32_e32 v64, v2
	v_mov_b32_e32 v65, v2
	v_mov_b32_e32 v66, v2
	v_mov_b32_e32 v67, v2
	v_mov_b32_e32 v68, v2
	v_mov_b32_e32 v69, v2
	v_mov_b32_e32 v70, v2
	v_mov_b32_e32 v71, v2
	v_mov_b32_e32 v72, v2
	v_mov_b32_e32 v73, v2
	v_mov_b32_e32 v82, v2
	v_mov_b32_e32 v83, v2
	v_mov_b32_e32 v84, v2
	v_mov_b32_e32 v85, v2
	v_mov_b32_e32 v86, v2
	v_mov_b32_e32 v87, v2
	v_mov_b32_e32 v88, v2
	v_mov_b32_e32 v89, v2
	v_mov_b32_e32 v98, v2
	v_mov_b32_e32 v99, v2
	v_mov_b32_e32 v100, v2
	v_mov_b32_e32 v101, v2
	v_mov_b32_e32 v102, v2
	v_mov_b32_e32 v103, v2
	v_mov_b32_e32 v104, v2
	v_mov_b32_e32 v105, v2
	v_mov_b32_e32 v114, v2
	v_mov_b32_e32 v115, v2
	v_mov_b32_e32 v116, v2
	v_mov_b32_e32 v117, v2
	v_mov_b32_e32 v118, v2
	v_mov_b32_e32 v119, v2
	v_mov_b32_e32 v120, v2
	v_mov_b32_e32 v121, v2
	v_mov_b32_e32 v74, v2
	v_mov_b32_e32 v75, v2
	v_mov_b32_e32 v76, v2
	v_mov_b32_e32 v77, v2
	v_mov_b32_e32 v78, v2
	v_mov_b32_e32 v79, v2
	v_mov_b32_e32 v80, v2
	v_mov_b32_e32 v81, v2
	v_mov_b32_e32 v90, v2
	v_mov_b32_e32 v91, v2
	v_mov_b32_e32 v92, v2
	v_mov_b32_e32 v93, v2
	v_mov_b32_e32 v94, v2
	v_mov_b32_e32 v95, v2
	v_mov_b32_e32 v96, v2
	v_mov_b32_e32 v97, v2
	v_mov_b32_e32 v106, v2
	v_mov_b32_e32 v107, v2
	v_mov_b32_e32 v108, v2
	v_mov_b32_e32 v109, v2
	v_mov_b32_e32 v110, v2
	v_mov_b32_e32 v111, v2
	v_mov_b32_e32 v112, v2
	v_mov_b32_e32 v113, v2
	v_mov_b32_e32 v122, v2
	v_mov_b32_e32 v123, v2
	v_mov_b32_e32 v124, v2
	v_mov_b32_e32 v125, v2
	v_mov_b32_e32 v126, v2
	v_mov_b32_e32 v127, v2
	v_mov_b32_e32 v128, v2
	v_mov_b32_e32 v129, v2
	s_cmp_eq_u32 s56, 1
	s_cbranch_scc1 .LBB0_985
.Lpeel_p3:
	s_add_u32 s44, s42, 0xfffc0080
	s_addc_u32 s45, s43, -1
	s_add_i32 s62, 0, 0x10000
	s_cmp_eq_u32 s61, 12
	s_cselect_b32 s47, s15, s45
	s_cselect_b32 s46, s35, s44
	v_add_u32_e32 v144, s62, v148
	s_cselect_b32 s45, s13, s60
	s_cselect_b32 s44, s58, s59
	s_add_i32 s64, 0, 0x14000
	ds_read_b128 v[140:143], v144
	ds_read_b128 v[150:153], v144 offset:1024
	ds_read_b128 v[154:157], v144 offset:2048
	ds_read_b128 v[158:161], v144 offset:3072
	v_add_u32_e32 v144, s64, v148
	ds_read_b128 v[162:165], v144
	ds_read_b128 v[166:169], v144 offset:1024
	ds_read_b128 v[182:185], v144 offset:2048
	ds_read_b128 v[186:189], v144 offset:3072
	v_lshl_add_u64 v[144:145], s[42:43], 0, v[136:137]
	s_add_i32 m0, s49, 0xc000
	ds_read_b128 v[190:193], v149
	ds_read_b128 v[194:197], v149 offset:1024
	ds_read_b128 v[198:201], v149 offset:2048
	ds_read_b128 v[202:205], v149 offset:3072
	ds_read_b128 v[206:209], v149 offset:4096
	ds_read_b128 v[210:213], v149 offset:5120
	ds_read_b128 v[214:217], v149 offset:6144
	ds_read_b128 v[232:235], v149 offset:7168
	global_load_lds_dwordx4 v[144:145], off
	v_lshl_add_u64 v[144:145], s[42:43], 0, v[138:139]
	s_add_i32 m0, s49, 0xe000
	s_nop 0
	global_load_lds_dwordx4 v[144:145], off
	s_waitcnt lgkmcnt(0)
	s_barrier
; #define PG8_STAGE(bufoff, gbase, voff) do { _Pragma("unroll") for (int _i = 0; _i < 2; ++_i) \
;         __builtin_amdgcn_global_load_lds((const unsigned*)((const char*)(gbase) + (voff)[_i]), (PG8_LAS unsigned*)(lds + (bufoff) + ldsw + _i * 8192), 16, 0, 0); } while (0)
; #define PG8_LDA(dst, b, h) do { _Pragma("unroll") for (int m = 0; m < 4; ++m) _Pragma("unroll") for (int k = 0; k < 2; ++k) dst[m][k] = *(const PG8_LAS bf16x8*)(lds + PG8_SA(b, h) + aoff + m * 2048 + k * 1024); } while (0)
; #define PG8_MMA(ai, bj, At, Bt) do { __builtin_amdgcn_s_setprio(1); _Pragma("unroll") for (int m = 0; m < 4; ++m) _Pragma("unroll") for (int n = 0; n < 2; ++n) _Pragma("unroll") for (int k = 0; k < 2; ++k) \
;         acc[ai][bj][m][n] = __builtin_amdgcn_mfma_f32_16x16x32_bf16(Bt[n][k], At[m][k], acc[ai][bj][m][n], 0, 0, 0); __builtin_amdgcn_s_setprio(0); } while (0)
; #define PG8_WAIT_V(n) asm volatile("s_waitcnt vmcnt(" #n ")" ::: "memory")
; #define PG8_WAIT_L(n) asm volatile("s_waitcnt lgkmcnt(" #n ")" ::: "memory")
; #define PG8_BAR __builtin_amdgcn_s_barrier()
; #define PG8_SCHED __builtin_amdgcn_sched_barrier(0)
; template <class Epi, class Sched, bool ALIGN_EPI = false, bool SP2 = false>
; __device__ __forceinline__ void gemm_phase(PG8_LAS unsigned char* lds, const Gemm g, const Sched& S, const Epi& E) {
;     ...
;             PG8_WAIT_V(8); PG8_WAIT_L(0); PG8_BAR; PG8_MMA(0, 0, At, B0); PG8_MMA(0, 1, At, B1); PG8_BAR; PG8_SCHED;
;             PG8_LDA(At, 0, 1); PG8_STAGE(PG8_SB(0, 0), b2, voffB); PG8_STAGE(PG8_SB(0, 1), b2 + hstep, voffB); PG8_STAGE(PG8_SA(0, 0), a2, voffA);
;             PG8_WAIT_V(8); PG8_WAIT_L(0); PG8_BAR; PG8_MMA(1, 0, At, B0); PG8_MMA(1, 1, At, B1); PG8_BAR; PG8_SCHED;
	s_setprio 1
	s_waitcnt lgkmcnt(0)
	v_mfma_f32_16x16x32_bf16 v[126:129], v[140:143], v[190:193], v[126:129]
	v_mfma_f32_16x16x32_bf16 v[122:125], v[154:157], v[190:193], v[122:125]
	v_mfma_f32_16x16x32_bf16 v[110:113], v[140:143], v[198:201], v[110:113]
	v_mfma_f32_16x16x32_bf16 v[106:109], v[154:157], v[198:201], v[106:109]
	v_mfma_f32_16x16x32_bf16 v[94:97], v[140:143], v[206:209], v[94:97]
	v_mfma_f32_16x16x32_bf16 v[90:93], v[154:157], v[206:209], v[90:93]
	v_mfma_f32_16x16x32_bf16 v[78:81], v[140:143], v[214:217], v[78:81]
	v_mfma_f32_16x16x32_bf16 v[74:77], v[154:157], v[214:217], v[74:77]
	v_mfma_f32_16x16x32_bf16 v[126:129], v[150:153], v[194:197], v[126:129]
	v_mfma_f32_16x16x32_bf16 v[122:125], v[158:161], v[194:197], v[122:125]
	v_mfma_f32_16x16x32_bf16 v[110:113], v[150:153], v[202:205], v[110:113]
	v_mfma_f32_16x16x32_bf16 v[106:109], v[158:161], v[202:205], v[106:109]
	v_mfma_f32_16x16x32_bf16 v[94:97], v[150:153], v[210:213], v[94:97]
	v_mfma_f32_16x16x32_bf16 v[90:93], v[158:161], v[210:213], v[90:93]
	v_mfma_f32_16x16x32_bf16 v[78:81], v[150:153], v[232:235], v[78:81]
	v_mfma_f32_16x16x32_bf16 v[74:77], v[158:161], v[232:235], v[74:77]
	s_setprio 0
	s_setprio 1
	v_mfma_f32_16x16x32_bf16 v[118:121], v[162:165], v[190:193], v[118:121]
	v_mfma_f32_16x16x32_bf16 v[114:117], v[182:185], v[190:193], v[114:117]
	v_mfma_f32_16x16x32_bf16 v[102:105], v[162:165], v[198:201], v[102:105]
	v_mfma_f32_16x16x32_bf16 v[98:101], v[182:185], v[198:201], v[98:101]
	v_mfma_f32_16x16x32_bf16 v[86:89], v[162:165], v[206:209], v[86:89]
	v_mfma_f32_16x16x32_bf16 v[82:85], v[182:185], v[206:209], v[82:85]
	v_mfma_f32_16x16x32_bf16 v[70:73], v[162:165], v[214:217], v[70:73]
	v_mfma_f32_16x16x32_bf16 v[66:69], v[182:185], v[214:217], v[66:69]
	v_mfma_f32_16x16x32_bf16 v[118:121], v[166:169], v[194:197], v[118:121]
	v_mfma_f32_16x16x32_bf16 v[114:117], v[186:189], v[194:197], v[114:117]
	v_mfma_f32_16x16x32_bf16 v[102:105], v[166:169], v[202:205], v[102:105]
	v_mfma_f32_16x16x32_bf16 v[98:101], v[186:189], v[202:205], v[98:101]
	v_mfma_f32_16x16x32_bf16 v[86:89], v[166:169], v[210:213], v[86:89]
	v_mfma_f32_16x16x32_bf16 v[82:85], v[186:189], v[210:213], v[82:85]
	v_mfma_f32_16x16x32_bf16 v[70:73], v[166:169], v[232:235], v[70:73]
	v_mfma_f32_16x16x32_bf16 v[66:69], v[186:189], v[232:235], v[66:69]
	s_setprio 0
	s_barrier
	s_add_i32 s62, s62, s48
	v_lshl_add_u64 v[144:145], s[44:45], 0, v[0:1]
	s_mov_b32 m0, s62
	ds_read_b128 v[190:193], v149 offset:16384
	ds_read_b128 v[194:197], v149 offset:17408
	ds_read_b128 v[198:201], v149 offset:18432
	ds_read_b128 v[202:205], v149 offset:19456
	ds_read_b128 v[206:209], v149 offset:20480
	ds_read_b128 v[210:213], v149 offset:21504
	ds_read_b128 v[214:217], v149 offset:22528
	ds_read_b128 v[232:235], v149 offset:23552
	global_load_lds_dwordx4 v[144:145], off
	s_add_i32 m0, s62, 0x2000
	s_add_u32 s62, s44, 0x40000
	v_lshl_add_u64 v[218:219], s[44:45], 0, v[130:131]
	s_addc_u32 s63, s45, 0
	s_add_i32 s64, s64, s48
	global_load_lds_dwordx4 v[218:219], off
	v_lshl_add_u64 v[236:237], s[62:63], 0, v[0:1]
	s_mov_b32 m0, s64
	v_lshl_add_u64 v[238:239], s[46:47], 0, v[132:133]
	global_load_lds_dwordx4 v[236:237], off
	v_lshl_add_u64 v[236:237], s[62:63], 0, v[130:131]
	s_add_i32 m0, s64, 0x2000
	s_nop 0
	global_load_lds_dwordx4 v[236:237], off
	v_lshl_add_u64 v[236:237], s[46:47], 0, v[134:135]
	s_mov_b32 m0, s49
	s_nop 0
	global_load_lds_dwordx4 v[236:237], off
	s_mov_b32 m0, s50
	s_nop 0
	global_load_lds_dwordx4 v[238:239], off
	s_waitcnt lgkmcnt(0)
	s_barrier
	s_setprio 1
	s_waitcnt lgkmcnt(0)
	v_mfma_f32_16x16x32_bf16 v[62:65], v[140:143], v[190:193], v[62:65]
	v_mfma_f32_16x16x32_bf16 v[58:61], v[154:157], v[190:193], v[58:61]
	v_mfma_f32_16x16x32_bf16 v[46:49], v[140:143], v[198:201], v[46:49]
	v_mfma_f32_16x16x32_bf16 v[42:45], v[154:157], v[198:201], v[42:45]
	v_mfma_f32_16x16x32_bf16 v[30:33], v[140:143], v[206:209], v[30:33]
	v_mfma_f32_16x16x32_bf16 v[26:29], v[154:157], v[206:209], v[26:29]
	v_mfma_f32_16x16x32_bf16 v[14:17], v[140:143], v[214:217], v[14:17]
	v_mfma_f32_16x16x32_bf16 v[10:13], v[154:157], v[214:217], v[10:13]
	v_mfma_f32_16x16x32_bf16 v[62:65], v[150:153], v[194:197], v[62:65]
	v_mfma_f32_16x16x32_bf16 v[58:61], v[158:161], v[194:197], v[58:61]
	v_mfma_f32_16x16x32_bf16 v[46:49], v[150:153], v[202:205], v[46:49]
	v_mfma_f32_16x16x32_bf16 v[42:45], v[158:161], v[202:205], v[42:45]
	v_mfma_f32_16x16x32_bf16 v[30:33], v[150:153], v[210:213], v[30:33]
	v_mfma_f32_16x16x32_bf16 v[26:29], v[158:161], v[210:213], v[26:29]
	v_mfma_f32_16x16x32_bf16 v[14:17], v[150:153], v[232:235], v[14:17]
	v_mfma_f32_16x16x32_bf16 v[10:13], v[158:161], v[232:235], v[10:13]
	s_setprio 0
	s_setprio 1
	v_mfma_f32_16x16x32_bf16 v[54:57], v[162:165], v[190:193], v[54:57]
	v_mfma_f32_16x16x32_bf16 v[50:53], v[182:185], v[190:193], v[50:53]
	v_mfma_f32_16x16x32_bf16 v[38:41], v[162:165], v[198:201], v[38:41]
	v_mfma_f32_16x16x32_bf16 v[34:37], v[182:185], v[198:201], v[34:37]
	v_mfma_f32_16x16x32_bf16 v[22:25], v[162:165], v[206:209], v[22:25]
	v_mfma_f32_16x16x32_bf16 v[18:21], v[182:185], v[206:209], v[18:21]
	v_mfma_f32_16x16x32_bf16 v[6:9], v[162:165], v[214:217], v[6:9]
	v_mfma_f32_16x16x32_bf16 v[2:5], v[182:185], v[214:217], v[2:5]
	v_mfma_f32_16x16x32_bf16 v[54:57], v[166:169], v[194:197], v[54:57]
	v_mfma_f32_16x16x32_bf16 v[50:53], v[186:189], v[194:197], v[50:53]
	v_mfma_f32_16x16x32_bf16 v[38:41], v[166:169], v[202:205], v[38:41]
	v_mfma_f32_16x16x32_bf16 v[34:37], v[186:189], v[202:205], v[34:37]
	v_mfma_f32_16x16x32_bf16 v[22:25], v[166:169], v[210:213], v[22:25]
	v_mfma_f32_16x16x32_bf16 v[18:21], v[186:189], v[210:213], v[18:21]
	v_mfma_f32_16x16x32_bf16 v[6:9], v[166:169], v[232:235], v[6:9]
	v_mfma_f32_16x16x32_bf16 v[2:5], v[186:189], v[232:235], v[2:5]
	s_setprio 0
	s_barrier
; #define PG8_STAGE(bufoff, gbase, voff) do { _Pragma("unroll") for (int _i = 0; _i < 2; ++_i) \
;         __builtin_amdgcn_global_load_lds((const unsigned*)((const char*)(gbase) + (voff)[_i]), (PG8_LAS unsigned*)(lds + (bufoff) + ldsw + _i * 8192), 16, 0, 0); } while (0)
; #define PG8_LDA(dst, b, h) do { _Pragma("unroll") for (int m = 0; m < 4; ++m) _Pragma("unroll") for (int k = 0; k < 2; ++k) dst[m][k] = *(const PG8_LAS bf16x8*)(lds + PG8_SA(b, h) + aoff + m * 2048 + k * 1024); } while (0)
; #define PG8_LDB(dst, b, h) do { _Pragma("unroll") for (int n = 0; n < 2; ++n) _Pragma("unroll") for (int k = 0; k < 2; ++k) dst[n][k] = *(const PG8_LAS bf16x8*)(lds + PG8_SB(b, h) + boff + n * 2048 + k * 1024); } while (0)
; #define PG8_MMA(ai, bj, At, Bt) do { __builtin_amdgcn_s_setprio(1); _Pragma("unroll") for (int m = 0; m < 4; ++m) _Pragma("unroll") for (int n = 0; n < 2; ++n) _Pragma("unroll") for (int k = 0; k < 2; ++k) \
;         acc[ai][bj][m][n] = __builtin_amdgcn_mfma_f32_16x16x32_bf16(Bt[n][k], At[m][k], acc[ai][bj][m][n], 0, 0, 0); __builtin_amdgcn_s_setprio(0); } while (0)
; #define PG8_WAIT_V(n) asm volatile("s_waitcnt vmcnt(" #n ")" ::: "memory")
; #define PG8_WAIT_L(n) asm volatile("s_waitcnt lgkmcnt(" #n ")" ::: "memory")
; #define PG8_BAR __builtin_amdgcn_s_barrier()
; #define PG8_SCHED __builtin_amdgcn_sched_barrier(0)
; template <class Epi, class Sched, bool ALIGN_EPI = false, bool SP2 = false>
; __device__ __forceinline__ void gemm_phase(PG8_LAS unsigned char* lds, const Gemm g, const Sched& S, const Epi& E) {
;     ...
;             PG8_LDB(B0, 1, 0); PG8_LDB(B1, 1, 1); PG8_SCHED; PG8_LDA(At, 1, 0); PG8_STAGE(PG8_SA(0, 1), a2 + hstep, voffA);
;             PG8_WAIT_V(8); PG8_WAIT_L(0); PG8_BAR; PG8_MMA(0, 0, At, B0); PG8_MMA(0, 1, At, B1); PG8_BAR; PG8_SCHED;
	s_add_i32 s62, 0, 0x18000
	s_add_i32 s63, 0, 0x1c000
	v_add_u32_e32 v158, s62, v148
	v_add_u32_e32 v186, s63, v148
	ds_read_b128 v[140:143], v158
	ds_read_b128 v[150:153], v158 offset:1024
	ds_read_b128 v[154:157], v158 offset:2048
	ds_read_b128 v[158:161], v158 offset:3072
	ds_read_b128 v[162:165], v186
	ds_read_b128 v[166:169], v186 offset:1024
	ds_read_b128 v[182:185], v186 offset:2048
	ds_read_b128 v[186:189], v186 offset:3072
	s_add_u32 s46, s46, 0x40000
	s_addc_u32 s47, s47, 0
	s_mov_b32 m0, s51
	v_lshl_add_u64 v[240:241], s[46:47], 0, v[134:135]
	ds_read_b128 v[190:193], v149 offset:32768
	ds_read_b128 v[194:197], v149 offset:33792
	ds_read_b128 v[198:201], v149 offset:34816
	ds_read_b128 v[202:205], v149 offset:35840
	ds_read_b128 v[206:209], v149 offset:36864
	ds_read_b128 v[210:213], v149 offset:37888
	ds_read_b128 v[214:217], v149 offset:38912
	ds_read_b128 v[232:235], v149 offset:39936
	global_load_lds_dwordx4 v[240:241], off
	v_lshl_add_u64 v[240:241], s[46:47], 0, v[132:133]
	s_mov_b32 m0, s52
	s_nop 0
	global_load_lds_dwordx4 v[240:241], off
	s_waitcnt vmcnt(8)
	s_waitcnt lgkmcnt(0)
	s_barrier
	s_setprio 1
	s_waitcnt lgkmcnt(0)
	v_mfma_f32_16x16x32_bf16 v[126:129], v[140:143], v[190:193], v[126:129]
	v_mfma_f32_16x16x32_bf16 v[122:125], v[154:157], v[190:193], v[122:125]
	v_mfma_f32_16x16x32_bf16 v[110:113], v[140:143], v[198:201], v[110:113]
	v_mfma_f32_16x16x32_bf16 v[106:109], v[154:157], v[198:201], v[106:109]
	v_mfma_f32_16x16x32_bf16 v[94:97], v[140:143], v[206:209], v[94:97]
	v_mfma_f32_16x16x32_bf16 v[90:93], v[154:157], v[206:209], v[90:93]
	v_mfma_f32_16x16x32_bf16 v[78:81], v[140:143], v[214:217], v[78:81]
	v_mfma_f32_16x16x32_bf16 v[74:77], v[154:157], v[214:217], v[74:77]
	v_mfma_f32_16x16x32_bf16 v[126:129], v[150:153], v[194:197], v[126:129]
	v_mfma_f32_16x16x32_bf16 v[122:125], v[158:161], v[194:197], v[122:125]
	v_mfma_f32_16x16x32_bf16 v[110:113], v[150:153], v[202:205], v[110:113]
	v_mfma_f32_16x16x32_bf16 v[106:109], v[158:161], v[202:205], v[106:109]
	v_mfma_f32_16x16x32_bf16 v[94:97], v[150:153], v[210:213], v[94:97]
	v_mfma_f32_16x16x32_bf16 v[90:93], v[158:161], v[210:213], v[90:93]
	v_mfma_f32_16x16x32_bf16 v[78:81], v[150:153], v[232:235], v[78:81]
	v_mfma_f32_16x16x32_bf16 v[74:77], v[158:161], v[232:235], v[74:77]
	s_setprio 0
	s_setprio 1
	v_mfma_f32_16x16x32_bf16 v[118:121], v[162:165], v[190:193], v[118:121]
	v_mfma_f32_16x16x32_bf16 v[114:117], v[182:185], v[190:193], v[114:117]
	v_mfma_f32_16x16x32_bf16 v[102:105], v[162:165], v[198:201], v[102:105]
	v_mfma_f32_16x16x32_bf16 v[98:101], v[182:185], v[198:201], v[98:101]
	v_mfma_f32_16x16x32_bf16 v[86:89], v[162:165], v[206:209], v[86:89]
	v_mfma_f32_16x16x32_bf16 v[82:85], v[182:185], v[206:209], v[82:85]
	v_mfma_f32_16x16x32_bf16 v[70:73], v[162:165], v[214:217], v[70:73]
	v_mfma_f32_16x16x32_bf16 v[66:69], v[182:185], v[214:217], v[66:69]
	v_mfma_f32_16x16x32_bf16 v[118:121], v[166:169], v[194:197], v[118:121]
	v_mfma_f32_16x16x32_bf16 v[114:117], v[186:189], v[194:197], v[114:117]
	v_mfma_f32_16x16x32_bf16 v[102:105], v[166:169], v[202:205], v[102:105]
	v_mfma_f32_16x16x32_bf16 v[98:101], v[186:189], v[202:205], v[98:101]
	v_mfma_f32_16x16x32_bf16 v[86:89], v[166:169], v[210:213], v[86:89]
	v_mfma_f32_16x16x32_bf16 v[82:85], v[186:189], v[210:213], v[82:85]
	v_mfma_f32_16x16x32_bf16 v[70:73], v[166:169], v[232:235], v[70:73]
	v_mfma_f32_16x16x32_bf16 v[66:69], v[186:189], v[232:235], v[66:69]
	s_setprio 0
	s_barrier
; #define PG8_STAGE(bufoff, gbase, voff) do { _Pragma("unroll") for (int _i = 0; _i < 2; ++_i) \
;         __builtin_amdgcn_global_load_lds((const unsigned*)((const char*)(gbase) + (voff)[_i]), (PG8_LAS unsigned*)(lds + (bufoff) + ldsw + _i * 8192), 16, 0, 0); } while (0)
; #define PG8_LDA(dst, b, h) do { _Pragma("unroll") for (int m = 0; m < 4; ++m) _Pragma("unroll") for (int k = 0; k < 2; ++k) dst[m][k] = *(const PG8_LAS bf16x8*)(lds + PG8_SA(b, h) + aoff + m * 2048 + k * 1024); } while (0)
; #define PG8_MMA(ai, bj, At, Bt) do { __builtin_amdgcn_s_setprio(1); _Pragma("unroll") for (int m = 0; m < 4; ++m) _Pragma("unroll") for (int n = 0; n < 2; ++n) _Pragma("unroll") for (int k = 0; k < 2; ++k) \
;         acc[ai][bj][m][n] = __builtin_amdgcn_mfma_f32_16x16x32_bf16(Bt[n][k], At[m][k], acc[ai][bj][m][n], 0, 0, 0); __builtin_amdgcn_s_setprio(0); } while (0)
; #define PG8_WAIT_V(n) asm volatile("s_waitcnt vmcnt(" #n ")" ::: "memory")
; #define PG8_WAIT_L(n) asm volatile("s_waitcnt lgkmcnt(" #n ")" ::: "memory")
; #define PG8_BAR __builtin_amdgcn_s_barrier()
; #define PG8_SCHED __builtin_amdgcn_sched_barrier(0)
; template <class Epi, class Sched, bool ALIGN_EPI = false, bool SP2 = false>
; __device__ __forceinline__ void gemm_phase(PG8_LAS unsigned char* lds, const Gemm g, const Sched& S, const Epi& E) {
;     ...
;         for (int t = 0; t < nt; t += 2) {
;     ...
;             PG8_LDA(At, 1, 1); PG8_STAGE(PG8_SB(1, 0), b3, voffB); PG8_STAGE(PG8_SB(1, 1), b3 + hstep, voffB); PG8_STAGE(PG8_SA(1, 0), a3, voffA);
;             PG8_WAIT_V(8); PG8_WAIT_L(0); PG8_BAR; PG8_MMA(1, 0, At, B0); PG8_MMA(1, 1, At, B1); PG8_BAR; PG8_SCHED;
	s_add_i32 s46, s62, s48
	v_lshl_add_u64 v[144:145], v[144:145], 0, s[36:37]
	s_mov_b32 m0, s46
	ds_read_b128 v[190:193], v149 offset:49152
	ds_read_b128 v[194:197], v149 offset:50176
	ds_read_b128 v[198:201], v149 offset:51200
	ds_read_b128 v[202:205], v149 offset:52224
	ds_read_b128 v[206:209], v149 offset:53248
	ds_read_b128 v[210:213], v149 offset:54272
	ds_read_b128 v[214:217], v149 offset:55296
	ds_read_b128 v[232:235], v149 offset:56320
	global_load_lds_dwordx4 v[144:145], off
	s_add_i32 m0, s46, 0x2000
	s_add_u32 s44, s44, 0x40080
	v_lshl_add_u64 v[144:145], v[218:219], 0, s[36:37]
	s_addc_u32 s45, s45, 0
	s_add_i32 s46, s63, s48
	global_load_lds_dwordx4 v[144:145], off
	v_lshl_add_u64 v[144:145], s[44:45], 0, v[0:1]
	s_mov_b32 m0, s46
	s_nop 0
	global_load_lds_dwordx4 v[144:145], off
	v_lshl_add_u64 v[144:145], s[44:45], 0, v[130:131]
	s_add_i32 m0, s46, 0x2000
	s_nop 0
	global_load_lds_dwordx4 v[144:145], off
	v_lshl_add_u64 v[144:145], v[236:237], 0, s[36:37]
	s_mov_b32 m0, s54
	s_nop 0
	global_load_lds_dwordx4 v[144:145], off
	v_lshl_add_u64 v[144:145], v[238:239], 0, s[36:37]
	s_mov_b32 m0, s55
	s_nop 0
	global_load_lds_dwordx4 v[144:145], off
	s_waitcnt vmcnt(8)
	s_waitcnt lgkmcnt(0)
	s_barrier
	s_setprio 1
	s_waitcnt lgkmcnt(0)
	v_mfma_f32_16x16x32_bf16 v[62:65], v[140:143], v[190:193], v[62:65]
	v_mfma_f32_16x16x32_bf16 v[58:61], v[154:157], v[190:193], v[58:61]
	v_mfma_f32_16x16x32_bf16 v[46:49], v[140:143], v[198:201], v[46:49]
	v_mfma_f32_16x16x32_bf16 v[42:45], v[154:157], v[198:201], v[42:45]
	v_mfma_f32_16x16x32_bf16 v[30:33], v[140:143], v[206:209], v[30:33]
	v_mfma_f32_16x16x32_bf16 v[26:29], v[154:157], v[206:209], v[26:29]
	v_mfma_f32_16x16x32_bf16 v[14:17], v[140:143], v[214:217], v[14:17]
	v_mfma_f32_16x16x32_bf16 v[10:13], v[154:157], v[214:217], v[10:13]
	v_mfma_f32_16x16x32_bf16 v[62:65], v[150:153], v[194:197], v[62:65]
	v_mfma_f32_16x16x32_bf16 v[58:61], v[158:161], v[194:197], v[58:61]
	v_mfma_f32_16x16x32_bf16 v[46:49], v[150:153], v[202:205], v[46:49]
	v_mfma_f32_16x16x32_bf16 v[42:45], v[158:161], v[202:205], v[42:45]
	v_mfma_f32_16x16x32_bf16 v[30:33], v[150:153], v[210:213], v[30:33]
	v_mfma_f32_16x16x32_bf16 v[26:29], v[158:161], v[210:213], v[26:29]
	v_mfma_f32_16x16x32_bf16 v[14:17], v[150:153], v[232:235], v[14:17]
	v_mfma_f32_16x16x32_bf16 v[10:13], v[158:161], v[232:235], v[10:13]
	s_setprio 0
	s_setprio 1
	v_mfma_f32_16x16x32_bf16 v[54:57], v[162:165], v[190:193], v[54:57]
	v_mfma_f32_16x16x32_bf16 v[50:53], v[182:185], v[190:193], v[50:53]
	v_mfma_f32_16x16x32_bf16 v[38:41], v[162:165], v[198:201], v[38:41]
	v_mfma_f32_16x16x32_bf16 v[34:37], v[182:185], v[198:201], v[34:37]
	v_mfma_f32_16x16x32_bf16 v[22:25], v[162:165], v[206:209], v[22:25]
	v_mfma_f32_16x16x32_bf16 v[18:21], v[182:185], v[206:209], v[18:21]
	v_mfma_f32_16x16x32_bf16 v[6:9], v[162:165], v[214:217], v[6:9]
	v_mfma_f32_16x16x32_bf16 v[2:5], v[182:185], v[214:217], v[2:5]
	v_mfma_f32_16x16x32_bf16 v[54:57], v[166:169], v[194:197], v[54:57]
	v_mfma_f32_16x16x32_bf16 v[50:53], v[186:189], v[194:197], v[50:53]
	v_mfma_f32_16x16x32_bf16 v[38:41], v[166:169], v[202:205], v[38:41]
	v_mfma_f32_16x16x32_bf16 v[34:37], v[186:189], v[202:205], v[34:37]
	v_mfma_f32_16x16x32_bf16 v[22:25], v[166:169], v[210:213], v[22:25]
	v_mfma_f32_16x16x32_bf16 v[18:21], v[186:189], v[210:213], v[18:21]
	v_mfma_f32_16x16x32_bf16 v[6:9], v[166:169], v[232:235], v[6:9]
	v_mfma_f32_16x16x32_bf16 v[2:5], v[186:189], v[232:235], v[2:5]
	s_setprio 0
	s_barrier
	s_add_i32 s61, s61, 2
	s_add_u32 s42, s42, 0x100
	s_addc_u32 s43, s43, 0
	s_add_u32 s59, s59, 0x100
	s_addc_u32 s60, s60, 0
	s_cmp_gt_u32 s61, 13
	s_cbranch_scc0 .LBB0_985
	s_branch .Lafter_985

; #define PG8_BAR __builtin_amdgcn_s_barrier()
; template <class Epi, class Sched, bool ALIGN_EPI = false, bool SP2 = false>
; __device__ __forceinline__ void gemm_phase(PG8_LAS unsigned char* lds, const Gemm g, const Sched& S, const Epi& E) {
;     ...
;         if constexpr (ALIGN_EPI) { if (wr == 0) PG8_BAR; }
;         if constexpr (!Epi::AFTER_DRAIN) { E(acc, cur, wr, wc, fr, fq); S.done(cur); }
.Lafter_985:
	s_and_b64 vcc, exec, s[10:11]
	s_cbranch_vccz .LBB0_988
	s_barrier
